# MoBA combine loop rewritten: 5 loads per element issued together, next element prefetched in a second register set (was 5 serialized round trips)
# speedup vs baseline: 1.0026x; 1.0026x over previous
; __device__ __forceinline__ u32x4 pack8(const float* f) { u32x4 w; w.x = cvt_pk_bf16(f[0], f[1]); w.y = cvt_pk_bf16(f[2], f[3]); w.z = cvt_pk_bf16(f[4], f[5]); w.w = cvt_pk_bf16(f[6], f[7]); return w; }
; __device__ __forceinline__ void moba_combine_phase(int bsel, const bf16_t* Opart, const float* lse, bf16_t* AO, int gtid, int gthreads) {
;     for (int idx = gtid; idx < SEQ * 96; idx += gthreads) {
;         const int chunk = idx & 7, th = idx >> 3, h = th % 12, t = th / 12, own = t >> 8, nv = own < 3 ? own : 3;
;         const f32x4 ls = *(const f32x4*)(lse + (size_t)th * 4);
;         float wv[4] = {nv > 0 ? ls.x : -INFINITY, nv > 1 ? ls.y : -INFINITY, nv > 2 ? ls.z : -INFINITY, ls.w};
;         const float mx = fmaxf(fmaxf(wv[0], wv[1]), fmaxf(wv[2], wv[3]));
;         float tot = 0.f;
; #pragma unroll
;         for (int j = 0; j < 4; ++j) { wv[j] = __builtin_amdgcn_exp2f(wv[j] - mx); tot += wv[j]; }
;         const float inv = 1.0f / tot;
;         float o[8];
; #pragma unroll
;         for (int e = 0; e < 8; ++e) o[e] = 0.f;
; #pragma unroll
;         for (int j = 0; j < 4; ++j) { if (j < nv || j == 3) { float v[8]; unpack8(*(const u32x4*)(Opart + ((size_t)th * 4 + j) * 64 + chunk * 8), v); const float wj = wv[j] * inv;
; #pragma unroll
;             for (int e = 0; e < 8; ++e) o[e] += wj * v[e]; } }
;         *(u32x4*)(AO + (size_t)(bsel * SEQ + t) * 1024 + h * 64 + chunk * 8) = pack8(o);
;     }
.LBB0_872:
	s_andn2_b64 vcc, exec, s[24:25]
	s_cbranch_vccnz .LBB0_729
	s_waitcnt lgkmcnt(0)
	v_mov_b32_e32 v64, v136
	v_cmp_gt_i32_e32 vcc, 0x180000, v64
	s_and_saveexec_b64 s[24:25], vcc
	s_cbranch_execz .LBB0_884
	s_lshl_b32 s30, s30, 14
	v_add_u32_e32 v65, s70, v64
	v_min_i32_e32 v116, 0x17ffff, v64
	v_ashrrev_i32_e32 v117, 3, v116
	v_lshlrev_b32_e32 v182, 4, v117
	global_load_dwordx4 v[68:71], v182, s[86:87]
	v_and_b32_e32 v126, 7, v116
	v_lshlrev_b32_e32 v183, 9, v117
	v_lshl_or_b32 v183, v126, 4, v183
	global_load_dwordx4 v[72:75], v183, s[78:79]
	global_load_dwordx4 v[76:79], v183, s[78:79] offset:128
	global_load_dwordx4 v[80:83], v183, s[78:79] offset:256
	global_load_dwordx4 v[84:87], v183, s[78:79] offset:384
	v_min_i32_e32 v116, 0x17ffff, v65
	v_ashrrev_i32_e32 v117, 3, v116
	v_lshlrev_b32_e32 v184, 4, v117
	global_load_dwordx4 v[88:91], v184, s[86:87]
	v_and_b32_e32 v126, 7, v116
	v_lshlrev_b32_e32 v185, 9, v117
	v_lshl_or_b32 v185, v126, 4, v185
	global_load_dwordx4 v[92:95], v185, s[78:79]
	global_load_dwordx4 v[96:99], v185, s[78:79] offset:128
	global_load_dwordx4 v[100:103], v185, s[78:79] offset:256
	global_load_dwordx4 v[104:107], v185, s[78:79] offset:384
	s_waitcnt vmcnt(5)
.Lcmb_loop:
	v_cmp_gt_i32_e32 vcc, 0x180000, v64
	v_min_i32_e32 v116, 0x17ffff, v64
	s_mov_b64 s[26:27], vcc
	v_ashrrev_i32_e32 v117, 3, v116
	v_mul_hi_i32 v118, v117, s5
	v_ashrrev_i32_e32 v118, 1, v118
	v_ashrrev_i32_e32 v119, 8, v118
	v_cmp_lt_i32_e64 s[36:37], 2, v119
	v_cmp_lt_i32_e64 s[38:39], 1, v119
	v_cmp_lt_i32_e64 s[40:41], 0, v119
	v_mul_lo_u32 v181, v118, 12
	v_sub_u32_e32 v181, v117, v181
	v_and_b32_e32 v180, 7, v116
	v_lshlrev_b32_e32 v180, 4, v180
	v_lshl_add_u32 v180, v181, 7, v180
	v_add_u32_e32 v118, s30, v118
	v_lshl_add_u32 v180, v118, 11, v180
	v_cndmask_b32_e64 v122, v207, v70, s[36:37]
	v_cndmask_b32_e64 v120, v207, v68, s[40:41]
	v_cndmask_b32_e64 v121, v207, v69, s[38:39]
	v_max_f32_e32 v124, v122, v122
	v_max_f32_e32 v125, v71, v71
	v_max_f32_e32 v124, v124, v125
	v_max3_f32 v124, v120, v121, v124
	v_sub_f32_e32 v126, v120, v124
	v_exp_f32_e32 v128, v126
	v_sub_f32_e32 v126, v121, v124
	v_exp_f32_e32 v129, v126
	v_sub_f32_e32 v126, v122, v124
	v_exp_f32_e32 v130, v126
	v_sub_f32_e32 v126, v71, v124
	v_exp_f32_e32 v131, v126
	s_nop 0
	v_add_f32_e32 v132, 0, v128
	v_add_f32_e32 v132, v129, v132
	v_add_f32_e32 v132, v130, v132
	v_add_f32_e32 v132, v131, v132
	v_div_scale_f32 v133, s[42:43], v132, v132, 1.0
	v_rcp_f32_e32 v134, v133
	s_nop 0
	v_fma_f32 v135, -v133, v134, 1.0
	v_fmac_f32_e32 v134, v135, v134
	v_div_scale_f32 v135, vcc, 1.0, v132, 1.0
	v_mul_f32_e32 v148, v135, v134
	v_fma_f32 v149, -v133, v148, v135
	v_fmac_f32_e32 v148, v149, v134
	v_fma_f32 v133, -v133, v148, v135
	v_div_fmas_f32 v133, v133, v134, v148
	v_div_fixup_f32 v127, v133, v132, 1.0
	v_mul_f32_e32 v153, v128, v127
	v_cndmask_b32_e64 v152, 0, v72, s[40:41]
	v_lshlrev_b32_e32 v150, 16, v152
	v_and_b32_e32 v151, 0xffff0000, v152
	v_fma_f32 v172, v153, v150, 0
	v_fma_f32 v173, v153, v151, 0
	v_cndmask_b32_e64 v152, 0, v73, s[40:41]
	v_lshlrev_b32_e32 v150, 16, v152
	v_and_b32_e32 v151, 0xffff0000, v152
	v_fma_f32 v174, v153, v150, 0
	v_fma_f32 v175, v153, v151, 0
	v_cndmask_b32_e64 v152, 0, v74, s[40:41]
	v_lshlrev_b32_e32 v150, 16, v152
	v_and_b32_e32 v151, 0xffff0000, v152
	v_fma_f32 v176, v153, v150, 0
	v_fma_f32 v177, v153, v151, 0
	v_cndmask_b32_e64 v152, 0, v75, s[40:41]
	v_lshlrev_b32_e32 v150, 16, v152
	v_and_b32_e32 v151, 0xffff0000, v152
	v_fma_f32 v178, v153, v150, 0
	v_fma_f32 v179, v153, v151, 0
	v_mul_f32_e32 v153, v129, v127
	v_cndmask_b32_e64 v152, 0, v76, s[38:39]
	v_lshlrev_b32_e32 v150, 16, v152
	v_and_b32_e32 v151, 0xffff0000, v152
	v_fmac_f32_e32 v172, v153, v150
	v_fmac_f32_e32 v173, v153, v151
	v_cndmask_b32_e64 v152, 0, v77, s[38:39]
	v_lshlrev_b32_e32 v150, 16, v152
	v_and_b32_e32 v151, 0xffff0000, v152
	v_fmac_f32_e32 v174, v153, v150
	v_fmac_f32_e32 v175, v153, v151
	v_cndmask_b32_e64 v152, 0, v78, s[38:39]
	v_lshlrev_b32_e32 v150, 16, v152
	v_and_b32_e32 v151, 0xffff0000, v152
	v_fmac_f32_e32 v176, v153, v150
	v_fmac_f32_e32 v177, v153, v151
	v_cndmask_b32_e64 v152, 0, v79, s[38:39]
	v_lshlrev_b32_e32 v150, 16, v152
	v_and_b32_e32 v151, 0xffff0000, v152
	v_fmac_f32_e32 v178, v153, v150
	v_fmac_f32_e32 v179, v153, v151
	v_mul_f32_e32 v153, v130, v127
	v_cndmask_b32_e64 v152, 0, v80, s[36:37]
	v_lshlrev_b32_e32 v150, 16, v152
	v_and_b32_e32 v151, 0xffff0000, v152
	v_fmac_f32_e32 v172, v153, v150
	v_fmac_f32_e32 v173, v153, v151
	v_cndmask_b32_e64 v152, 0, v81, s[36:37]
	v_lshlrev_b32_e32 v150, 16, v152
	v_and_b32_e32 v151, 0xffff0000, v152
	v_fmac_f32_e32 v174, v153, v150
	v_fmac_f32_e32 v175, v153, v151
	v_cndmask_b32_e64 v152, 0, v82, s[36:37]
	v_lshlrev_b32_e32 v150, 16, v152
	v_and_b32_e32 v151, 0xffff0000, v152
	v_fmac_f32_e32 v176, v153, v150
	v_fmac_f32_e32 v177, v153, v151
	v_cndmask_b32_e64 v152, 0, v83, s[36:37]
	v_lshlrev_b32_e32 v150, 16, v152
	v_and_b32_e32 v151, 0xffff0000, v152
	v_fmac_f32_e32 v178, v153, v150
	v_fmac_f32_e32 v179, v153, v151
	v_mul_f32_e32 v153, v131, v127
	v_lshlrev_b32_e32 v150, 16, v84
	v_and_b32_e32 v151, 0xffff0000, v84
	v_fmac_f32_e32 v172, v153, v150
	v_fmac_f32_e32 v173, v153, v151
	v_lshlrev_b32_e32 v150, 16, v85
	v_and_b32_e32 v151, 0xffff0000, v85
	v_fmac_f32_e32 v174, v153, v150
	v_fmac_f32_e32 v175, v153, v151
	v_lshlrev_b32_e32 v150, 16, v86
	v_and_b32_e32 v151, 0xffff0000, v86
	v_fmac_f32_e32 v176, v153, v150
	v_fmac_f32_e32 v177, v153, v151
	v_lshlrev_b32_e32 v150, 16, v87
	v_and_b32_e32 v151, 0xffff0000, v87
	v_fmac_f32_e32 v178, v153, v150
	v_fmac_f32_e32 v179, v153, v151
	v_cvt_pk_bf16_f32 v108, v172, v173
	v_cvt_pk_bf16_f32 v109, v174, v175
	v_cvt_pk_bf16_f32 v110, v176, v177
	v_cvt_pk_bf16_f32 v111, v178, v179
	s_and_saveexec_b64 s[42:43], s[26:27]
	global_store_dwordx4 v180, v[108:111], s[80:81]
	s_mov_b64 exec, s[42:43]
	v_lshl_add_u32 v64, s70, 1, v64
	v_min_i32_e32 v116, 0x17ffff, v64
	v_ashrrev_i32_e32 v117, 3, v116
	v_lshlrev_b32_e32 v182, 4, v117
	global_load_dwordx4 v[68:71], v182, s[86:87]
	v_and_b32_e32 v126, 7, v116
	v_lshlrev_b32_e32 v183, 9, v117
	v_lshl_or_b32 v183, v126, 4, v183
	global_load_dwordx4 v[72:75], v183, s[78:79]
	global_load_dwordx4 v[76:79], v183, s[78:79] offset:128
	global_load_dwordx4 v[80:83], v183, s[78:79] offset:256
	global_load_dwordx4 v[84:87], v183, s[78:79] offset:384
	s_waitcnt vmcnt(6)
; __device__ __forceinline__ u32x4 pack8(const float* f) { u32x4 w; w.x = cvt_pk_bf16(f[0], f[1]); w.y = cvt_pk_bf16(f[2], f[3]); w.z = cvt_pk_bf16(f[4], f[5]); w.w = cvt_pk_bf16(f[6], f[7]); return w; }
; __device__ __forceinline__ void moba_combine_phase(int bsel, const bf16_t* Opart, const float* lse, bf16_t* AO, int gtid, int gthreads) {
;     for (int idx = gtid; idx < SEQ * 96; idx += gthreads) {
;         const int chunk = idx & 7, th = idx >> 3, h = th % 12, t = th / 12, own = t >> 8, nv = own < 3 ? own : 3;
;         const f32x4 ls = *(const f32x4*)(lse + (size_t)th * 4);
;         float wv[4] = {nv > 0 ? ls.x : -INFINITY, nv > 1 ? ls.y : -INFINITY, nv > 2 ? ls.z : -INFINITY, ls.w};
;         const float mx = fmaxf(fmaxf(wv[0], wv[1]), fmaxf(wv[2], wv[3]));
;         float tot = 0.f;
; #pragma unroll
;         for (int j = 0; j < 4; ++j) { wv[j] = __builtin_amdgcn_exp2f(wv[j] - mx); tot += wv[j]; }
;         const float inv = 1.0f / tot;
;         float o[8];
; #pragma unroll
;         for (int e = 0; e < 8; ++e) o[e] = 0.f;
; #pragma unroll
;         for (int j = 0; j < 4; ++j) { if (j < nv || j == 3) { float v[8]; unpack8(*(const u32x4*)(Opart + ((size_t)th * 4 + j) * 64 + chunk * 8), v); const float wj = wv[j] * inv;
; #pragma unroll
;             for (int e = 0; e < 8; ++e) o[e] += wj * v[e]; } }
;         *(u32x4*)(AO + (size_t)(bsel * SEQ + t) * 1024 + h * 64 + chunk * 8) = pack8(o);
;     }
	v_cmp_gt_i32_e32 vcc, 0x180000, v65
	v_min_i32_e32 v116, 0x17ffff, v65
	s_mov_b64 s[26:27], vcc
	v_ashrrev_i32_e32 v117, 3, v116
	v_mul_hi_i32 v118, v117, s5
	v_ashrrev_i32_e32 v118, 1, v118
	v_ashrrev_i32_e32 v119, 8, v118
	v_cmp_lt_i32_e64 s[36:37], 2, v119
	v_cmp_lt_i32_e64 s[38:39], 1, v119
	v_cmp_lt_i32_e64 s[40:41], 0, v119
	v_mul_lo_u32 v181, v118, 12
	v_sub_u32_e32 v181, v117, v181
	v_and_b32_e32 v180, 7, v116
	v_lshlrev_b32_e32 v180, 4, v180
	v_lshl_add_u32 v180, v181, 7, v180
	v_add_u32_e32 v118, s30, v118
	v_lshl_add_u32 v180, v118, 11, v180
	v_cndmask_b32_e64 v122, v207, v90, s[36:37]
	v_cndmask_b32_e64 v120, v207, v88, s[40:41]
	v_cndmask_b32_e64 v121, v207, v89, s[38:39]
	v_max_f32_e32 v124, v122, v122
	v_max_f32_e32 v125, v91, v91
	v_max_f32_e32 v124, v124, v125
	v_max3_f32 v124, v120, v121, v124
	v_sub_f32_e32 v126, v120, v124
	v_exp_f32_e32 v128, v126
	v_sub_f32_e32 v126, v121, v124
	v_exp_f32_e32 v129, v126
	v_sub_f32_e32 v126, v122, v124
	v_exp_f32_e32 v130, v126
	v_sub_f32_e32 v126, v91, v124
	v_exp_f32_e32 v131, v126
	s_nop 0
	v_add_f32_e32 v132, 0, v128
	v_add_f32_e32 v132, v129, v132
	v_add_f32_e32 v132, v130, v132
	v_add_f32_e32 v132, v131, v132
	v_div_scale_f32 v133, s[42:43], v132, v132, 1.0
	v_rcp_f32_e32 v134, v133
	s_nop 0
	v_fma_f32 v135, -v133, v134, 1.0
	v_fmac_f32_e32 v134, v135, v134
	v_div_scale_f32 v135, vcc, 1.0, v132, 1.0
	v_mul_f32_e32 v148, v135, v134
	v_fma_f32 v149, -v133, v148, v135
	v_fmac_f32_e32 v148, v149, v134
	v_fma_f32 v133, -v133, v148, v135
	v_div_fmas_f32 v133, v133, v134, v148
	v_div_fixup_f32 v127, v133, v132, 1.0
	v_mul_f32_e32 v153, v128, v127
	v_cndmask_b32_e64 v152, 0, v92, s[40:41]
	v_lshlrev_b32_e32 v150, 16, v152
	v_and_b32_e32 v151, 0xffff0000, v152
	v_fma_f32 v172, v153, v150, 0
	v_fma_f32 v173, v153, v151, 0
	v_cndmask_b32_e64 v152, 0, v93, s[40:41]
	v_lshlrev_b32_e32 v150, 16, v152
	v_and_b32_e32 v151, 0xffff0000, v152
	v_fma_f32 v174, v153, v150, 0
	v_fma_f32 v175, v153, v151, 0
	v_cndmask_b32_e64 v152, 0, v94, s[40:41]
	v_lshlrev_b32_e32 v150, 16, v152
	v_and_b32_e32 v151, 0xffff0000, v152
	v_fma_f32 v176, v153, v150, 0
	v_fma_f32 v177, v153, v151, 0
	v_cndmask_b32_e64 v152, 0, v95, s[40:41]
	v_lshlrev_b32_e32 v150, 16, v152
	v_and_b32_e32 v151, 0xffff0000, v152
	v_fma_f32 v178, v153, v150, 0
	v_fma_f32 v179, v153, v151, 0
	v_mul_f32_e32 v153, v129, v127
	v_cndmask_b32_e64 v152, 0, v96, s[38:39]
	v_lshlrev_b32_e32 v150, 16, v152
	v_and_b32_e32 v151, 0xffff0000, v152
	v_fmac_f32_e32 v172, v153, v150
	v_fmac_f32_e32 v173, v153, v151
	v_cndmask_b32_e64 v152, 0, v97, s[38:39]
	v_lshlrev_b32_e32 v150, 16, v152
	v_and_b32_e32 v151, 0xffff0000, v152
	v_fmac_f32_e32 v174, v153, v150
	v_fmac_f32_e32 v175, v153, v151
	v_cndmask_b32_e64 v152, 0, v98, s[38:39]
	v_lshlrev_b32_e32 v150, 16, v152
	v_and_b32_e32 v151, 0xffff0000, v152
	v_fmac_f32_e32 v176, v153, v150
	v_fmac_f32_e32 v177, v153, v151
	v_cndmask_b32_e64 v152, 0, v99, s[38:39]
	v_lshlrev_b32_e32 v150, 16, v152
	v_and_b32_e32 v151, 0xffff0000, v152
	v_fmac_f32_e32 v178, v153, v150
	v_fmac_f32_e32 v179, v153, v151
	v_mul_f32_e32 v153, v130, v127
	v_cndmask_b32_e64 v152, 0, v100, s[36:37]
	v_lshlrev_b32_e32 v150, 16, v152
	v_and_b32_e32 v151, 0xffff0000, v152
	v_fmac_f32_e32 v172, v153, v150
	v_fmac_f32_e32 v173, v153, v151
	v_cndmask_b32_e64 v152, 0, v101, s[36:37]
	v_lshlrev_b32_e32 v150, 16, v152
	v_and_b32_e32 v151, 0xffff0000, v152
	v_fmac_f32_e32 v174, v153, v150
	v_fmac_f32_e32 v175, v153, v151
	v_cndmask_b32_e64 v152, 0, v102, s[36:37]
	v_lshlrev_b32_e32 v150, 16, v152
	v_and_b32_e32 v151, 0xffff0000, v152
	v_fmac_f32_e32 v176, v153, v150
	v_fmac_f32_e32 v177, v153, v151
	v_cndmask_b32_e64 v152, 0, v103, s[36:37]
	v_lshlrev_b32_e32 v150, 16, v152
	v_and_b32_e32 v151, 0xffff0000, v152
	v_fmac_f32_e32 v178, v153, v150
	v_fmac_f32_e32 v179, v153, v151
	v_mul_f32_e32 v153, v131, v127
	v_lshlrev_b32_e32 v150, 16, v104
	v_and_b32_e32 v151, 0xffff0000, v104
	v_fmac_f32_e32 v172, v153, v150
	v_fmac_f32_e32 v173, v153, v151
	v_lshlrev_b32_e32 v150, 16, v105
	v_and_b32_e32 v151, 0xffff0000, v105
	v_fmac_f32_e32 v174, v153, v150
	v_fmac_f32_e32 v175, v153, v151
	v_lshlrev_b32_e32 v150, 16, v106
	v_and_b32_e32 v151, 0xffff0000, v106
	v_fmac_f32_e32 v176, v153, v150
	v_fmac_f32_e32 v177, v153, v151
	v_lshlrev_b32_e32 v150, 16, v107
	v_and_b32_e32 v151, 0xffff0000, v107
	v_fmac_f32_e32 v178, v153, v150
	v_fmac_f32_e32 v179, v153, v151
	v_cvt_pk_bf16_f32 v112, v172, v173
	v_cvt_pk_bf16_f32 v113, v174, v175
	v_cvt_pk_bf16_f32 v114, v176, v177
	v_cvt_pk_bf16_f32 v115, v178, v179
	s_and_saveexec_b64 s[42:43], s[26:27]
	global_store_dwordx4 v180, v[112:115], s[80:81]
	s_mov_b64 exec, s[42:43]
	v_lshl_add_u32 v65, s70, 1, v65
	v_min_i32_e32 v116, 0x17ffff, v65
	v_ashrrev_i32_e32 v117, 3, v116
	v_lshlrev_b32_e32 v184, 4, v117
	global_load_dwordx4 v[88:91], v184, s[86:87]
	v_and_b32_e32 v126, 7, v116
	v_lshlrev_b32_e32 v185, 9, v117
	v_lshl_or_b32 v185, v126, 4, v185
	global_load_dwordx4 v[92:95], v185, s[78:79]
	global_load_dwordx4 v[96:99], v185, s[78:79] offset:128
	global_load_dwordx4 v[100:103], v185, s[78:79] offset:256
	global_load_dwordx4 v[104:107], v185, s[78:79] offset:384
	s_waitcnt vmcnt(6)
	v_cmp_gt_i32_e32 vcc, 0x180000, v64
	s_cbranch_vccnz .Lcmb_loop
	s_waitcnt vmcnt(0)
